# attention loops: running max baked into the QK MFMA C input (no per-score subtraction before exp2 in the common path); rescale path applies the correction
# speedup vs baseline: 1.0109x; 1.0056x over previous
; #define LAS __attribute__((address_space(3)))
; template <int DQ>
; __device__ __forceinline__ void attn_unit(LAS unsigned char* lds, const AttnDesc& A, int tid_in, int wid, int lane_in) {
;     constexpr int KSTR = (DQ + 8) * 2, NS = DQ / 16;
;     int tid = tid_in; asm volatile("" : "+v"(tid));
;     const int lane = tid & 63; (void)lane_in;
;     const int r32 = lane & 31, h = lane >> 5;
;     const int nt = A.nloc + 4;
;     bf16x8 qf[NS];
; #pragma unroll
;     for (int s = 0; s < NS; ++s) qf[s] = *(const bf16x8*)(A.q + (size_t)r32 * A.ldq + 16 * s + 8 * h);
;     f32x16 o0, o1;
; #pragma unroll
;     for (int r = 0; r < 16; ++r) { o0[r] = 0.f; o1[r] = 0.f; }
;     float mrun = -1e30f, lrun = 0.f;
;     f32x16 zero16;
; #pragma unroll
;     for (int r = 0; r < 16; ++r) zero16[r] = 0.f;
;     asm volatile("" : "+v"(zero16));
;     const int skey = tid >> 3, sch = tid & 7;
;     u32x4 kreg, vreg, krreg = (u32x4){0u, 0u, 0u, 0u};
;     {
;         const int row0 = (0 < A.nloc) ? A.loc_row0 : A.ctx_row0;
;         kreg = *(const u32x4*)(A.k + (size_t)(row0 + skey) * A.ldk + 8 * sch);
;         vreg = *(const u32x4*)(A.v + (size_t)(row0 + skey) * A.ldv + 8 * sch);
;         if (DQ == 96 && tid < 256) krreg = *(const u32x4*)(A.kr + (size_t)(row0 + (tid >> 2)) * A.ldkr + 8 * (tid & 3));
;     }
;     const LAS float* rpbl = (const LAS float*)(lds + ATT_RPB);
;     const int vtr_off = ((lane & 15) >> 2) * 64 + (16 * ((lane >> 4) & 1) + 4 * (lane & 3)) * 2 + 4 * h * 64;
;     ...
;                 const int qc = 32 * (wid & 1) + r32;
;                 const int w0 = min(max(qc - 8, 0), 48);
;                 const int rbase = (A.a0 + t - A.a1 + 7) * 31;
; #pragma unroll
;                 for (int r = 0; r < 16; ++r) {
;                     const int kc = (r & 3) + 8 * (r >> 2) + 4 * h;
;                     { const int dc = min(max(kc - qc + 15, 0), 30); const bool ok = (unsigned)(kc - w0) < 16u; const float bv = rpbl[rbase + dc]; s0[r] = ok ? s0[r] + bv : -1e30f; }
.LBB0_54:
	v_mov_b32_e32 v32, v154
	v_mov_b32_e32 v157, v1
	v_and_b32_e32 v165, 31, v32
	v_mul_u32_u24_e32 v0, s40, v165
	v_bfe_u32 v33, v32, 5, 1
	v_lshlrev_b32_e32 v0, 1, v0
	v_lshl_add_u64 v[2:3], s[0:1], 0, v[0:1]
	v_lshlrev_b32_e32 v156, 4, v33
	v_lshl_add_u64 v[2:3], v[2:3], 0, v[156:157]
	s_waitcnt vmcnt(0)
	flat_load_dwordx4 v[130:133], v[2:3]
	flat_load_dwordx4 v[134:137], v[2:3] offset:32
	flat_load_dwordx4 v[138:141], v[2:3] offset:64
	flat_load_dwordx4 v[142:145], v[2:3] offset:96
	v_mov_b32_e32 v14, v1
	v_mov_b32_e32 v15, v1
	v_mov_b32_e32 v0, v1
	v_mov_b32_e32 v2, v1
	v_mov_b32_e32 v3, v1
	v_mov_b32_e32 v4, v1
	v_mov_b32_e32 v5, v1
	v_mov_b32_e32 v6, v1
	v_mov_b32_e32 v7, v1
	v_mov_b32_e32 v8, v1
	v_mov_b32_e32 v9, v1
	v_mov_b32_e32 v10, v1
	v_mov_b32_e32 v11, v1
	v_mov_b32_e32 v12, v1
	v_mov_b32_e32 v13, v1
	v_mov_b64_e32 v[30:31], v[14:15]
	v_mov_b64_e32 v[28:29], v[12:13]
	v_mov_b64_e32 v[26:27], v[10:11]
	v_mov_b64_e32 v[24:25], v[8:9]
	v_mov_b64_e32 v[22:23], v[6:7]
	v_mov_b64_e32 v[20:21], v[4:5]
	v_mov_b64_e32 v[18:19], v[2:3]
	v_mov_b64_e32 v[16:17], v[0:1]
	s_mov_b32 s41, 0
	s_cmp_lt_i32 s59, -3
	v_lshlrev_b32_e32 v157, 2, v33
	s_cbranch_scc1 .LBB0_137
	s_lshl_b32 s60, s8, 8
	s_add_i32 s56, s59, 4
	s_add_i32 s60, s60, 0x8000
	v_ashrrev_i32_e32 v38, 3, v32
	v_lshlrev_b32_e32 v39, 4, v32
	v_and_b32_e32 v34, 16, v32
	v_lshlrev_b32_e32 v35, 2, v32
	s_cmp_gt_i32 s59, 0
	v_lshlrev_b32_e32 v32, 10, v32
	s_cselect_b32 s0, s57, s60
	v_and_b32_e32 v174, 0x1000, v32
	v_or_b32_e32 v32, s22, v165
	v_and_or_b32 v34, v35, 12, v34
	v_lshlrev_b32_e32 v172, 8, v33
	v_add_u32_e32 v33, s0, v38
	v_sub_u32_e64 v32, v32, 8 clamp
	v_lshlrev_b32_e32 v171, 1, v34
	v_mad_i64_i32 v[34:35], s[0:1], s40, v33, 0
	v_min_u32_e32 v32, 48, v32
	v_or_b32_e32 v33, 1, v157
	v_lshlrev_b64 v[34:35], 1, v[34:35]
	s_movk_i32 s0, 0x90
	v_sub_u32_e32 v33, v33, v32
	v_lshl_add_u64 v[36:37], s[50:51], 0, v[34:35]
	v_and_b32_e32 v158, 0x70, v39
	v_mov_b32_e32 v159, v1
	v_lshl_add_u64 v[34:35], s[48:49], 0, v[34:35]
	v_mul_lo_u32 v173, v38, s0
	v_cmp_gt_u32_e64 s[0:1], 16, v33
	v_or_b32_e32 v33, 33, v157
	v_lshl_add_u64 v[34:35], v[34:35], 0, v[158:159]
	v_writelane_b32 v255, s0, 12
	v_sub_u32_e32 v33, v33, v32
	flat_load_dwordx4 v[150:153], v[34:35]
	v_or_b32_e32 v34, 2, v157
	v_writelane_b32 v255, s1, 13
	v_cmp_gt_u32_e64 s[0:1], 16, v33
	v_sub_u32_e32 v33, v34, v32
	v_or_b32_e32 v35, 3, v157
	v_writelane_b32 v255, s0, 14
	v_lshl_add_u64 v[36:37], v[36:37], 0, v[158:159]
	flat_load_dwordx4 v[146:149], v[36:37]
	v_writelane_b32 v255, s1, 15
	v_cmp_gt_u32_e64 s[0:1], 16, v33
	v_or_b32_e32 v33, 34, v157
	v_sub_u32_e32 v33, v33, v32
	v_writelane_b32 v255, s0, 16
	v_or_b32_e32 v36, 8, v157
	v_or_b32_e32 v37, 9, v157
	v_writelane_b32 v255, s1, 17
	v_cmp_gt_u32_e64 s[0:1], 16, v33
	v_sub_u32_e32 v33, v35, v32
	v_and_b32_e32 v65, 0xc0, v39
	v_writelane_b32 v255, s0, 18
	v_and_b32_e32 v176, 48, v39
	v_or_b32_e32 v39, 10, v157
	v_writelane_b32 v255, s1, 19
	v_cmp_gt_u32_e64 s[0:1], 16, v33
	v_or_b32_e32 v33, 35, v157
	v_sub_u32_e32 v33, v33, v32
	v_writelane_b32 v255, s0, 20
	v_or_b32_e32 v40, 11, v157
	v_or_b32_e32 v41, 16, v157
	v_writelane_b32 v255, s1, 21
	v_cmp_gt_u32_e64 s[0:1], 16, v33
	v_sub_u32_e32 v33, v36, v32
	v_or_b32_e32 v42, 17, v157
	v_writelane_b32 v255, s0, 22
	v_or_b32_e32 v43, 18, v157
	v_or_b32_e32 v44, 19, v157
	v_writelane_b32 v255, s1, 23
	v_cmp_gt_u32_e64 s[0:1], 16, v33
	v_or_b32_e32 v33, 40, v157
	v_sub_u32_e32 v33, v33, v32
	v_writelane_b32 v255, s0, 24
	v_or_b32_e32 v45, 24, v157
	s_mov_b64 s[68:69], s[92:93]
	v_writelane_b32 v255, s1, 25
	v_cmp_gt_u32_e64 s[0:1], 16, v33
	v_sub_u32_e32 v33, v37, v32
	v_or_b32_e32 v46, 25, v157
	v_writelane_b32 v255, s0, 26
	s_mov_b64 s[70:71], s[94:95]
	v_or_b32_e32 v47, 26, v157
	v_writelane_b32 v255, s1, 27
	v_cmp_gt_u32_e64 s[0:1], 16, v33
	v_or_b32_e32 v33, 41, v157
	v_sub_u32_e32 v33, v33, v32
	v_writelane_b32 v255, s0, 28
	s_mov_b64 s[64:65], s[98:99]
	v_or_b32_e32 v48, 27, v157
	v_writelane_b32 v255, s1, 29
	v_cmp_gt_u32_e64 s[0:1], 16, v33
	v_sub_u32_e32 v33, v39, v32
	v_sub_u32_e32 v49, v157, v32
	v_writelane_b32 v255, s0, 30
	v_cmp_gt_u32_e64 s[72:73], 16, v49
	v_or_b32_e32 v49, 32, v157
	v_writelane_b32 v255, s1, 31
	v_cmp_gt_u32_e64 s[0:1], 16, v33
	v_or_b32_e32 v33, 42, v157
	v_sub_u32_e32 v33, v33, v32
	v_writelane_b32 v255, s0, 32
	s_cmp_eq_u32 s53, 1
	v_sub_u32_e32 v49, v49, v32
	v_writelane_b32 v255, s1, 33
	v_cmp_gt_u32_e64 s[0:1], 16, v33
	v_sub_u32_e32 v33, v40, v32
	s_cselect_b64 s[84:85], -1, 0
	v_writelane_b32 v255, s0, 34
	s_add_i32 s58, s61, 8
	s_cmp_eq_u32 s53, 2
	v_writelane_b32 v255, s1, 35
	v_cmp_gt_u32_e64 s[0:1], 16, v33
	v_or_b32_e32 v33, 43, v157
	v_sub_u32_e32 v33, v33, v32
	v_writelane_b32 v255, s0, 36
	v_readlane_b32 s18, v254, 50
	v_lshl_add_u64 v[160:161], s[48:49], 0, v[158:159]
	v_writelane_b32 v255, s1, 37
	v_cmp_gt_u32_e64 s[0:1], 16, v33
	v_sub_u32_e32 v33, v41, v32
	v_lshl_add_u64 v[162:163], s[50:51], 0, v[158:159]
	v_writelane_b32 v255, s0, 38
	s_cselect_b64 s[86:87], -1, 0
	s_add_i32 s63, s52, 0xffffff9f
	v_writelane_b32 v255, s1, 39
	v_cmp_gt_u32_e64 s[0:1], 16, v33
	v_or_b32_e32 v33, 48, v157
	v_sub_u32_e32 v33, v33, v32
	v_writelane_b32 v255, s0, 40
	s_add_i32 s80, s52, 0x41
	v_lshlrev_b32_e32 v175, 6, v38
	v_writelane_b32 v255, s1, 41
	v_cmp_gt_u32_e64 s[0:1], 16, v33
	v_sub_u32_e32 v33, v42, v32
	v_cmp_gt_u32_e64 s[74:75], 16, v49
	v_writelane_b32 v255, s0, 42
	v_add_u32_e32 v211, 64, v38
	v_mul_u32_u24_e32 v177, 0x90, v165
	v_writelane_b32 v255, s1, 43
	v_cmp_gt_u32_e64 s[0:1], 16, v33
	v_or_b32_e32 v33, 49, v157
	v_sub_u32_e32 v33, v33, v32
; template <int DQ>
; __device__ __forceinline__ void attn_unit(LAS unsigned char* lds, const AttnDesc& A, int tid_in, int wid, int lane_in) {
;     ...
;                 const int qc = 32 * (wid & 1) + r32;
;                 const int w0 = min(max(qc - 8, 0), 48);
;                 const int rbase = (A.a0 + t - A.a1 + 7) * 31;
; #pragma unroll
;                 for (int r = 0; r < 16; ++r) {
;                     const int kc = (r & 3) + 8 * (r >> 2) + 4 * h;
;                     { const int dc = min(max(kc - qc + 15, 0), 30); const bool ok = (unsigned)(kc - w0) < 16u; const float bv = rpbl[rbase + dc]; s0[r] = ok ? s0[r] + bv : -1e30f; }
;                     { const int kc2 = kc + 32; const int dc = min(max(kc2 - qc + 15, 0), 30); const bool ok = (unsigned)(kc2 - w0) < 16u; const float bv = rpbl[rbase + dc]; s1[r] = ok ? s1[r] + bv : -1e30f; }
;                 }
	v_writelane_b32 v255, s0, 44
	v_mov_b32_e32 v212, 0xf149f2ca
	v_mov_b32_e32 v213, 0xf149f2ca
	v_mov_b32_e32 v64, 0
	v_writelane_b32 v255, s1, 45
	v_cmp_gt_u32_e64 s[0:1], 16, v33
	v_sub_u32_e32 v33, v43, v32
	s_mov_b32 s82, 0
	v_writelane_b32 v255, s0, 46
	s_nop 1
	v_writelane_b32 v255, s1, 47
	v_cmp_gt_u32_e64 s[0:1], 16, v33
	v_or_b32_e32 v33, 50, v157
	v_sub_u32_e32 v33, v33, v32
	v_writelane_b32 v255, s0, 48
	s_nop 1
	v_writelane_b32 v255, s1, 49
	v_cmp_gt_u32_e64 s[0:1], 16, v33
	v_sub_u32_e32 v33, v44, v32
	v_cmp_gt_u32_e64 s[88:89], 16, v33
	v_or_b32_e32 v33, 51, v157
	v_sub_u32_e32 v33, v33, v32
	v_cmp_gt_u32_e64 s[90:91], 16, v33
	v_sub_u32_e32 v33, v45, v32
	v_cmp_gt_u32_e64 s[92:93], 16, v33
	v_or_b32_e32 v33, 56, v157
	v_sub_u32_e32 v33, v33, v32
	v_cmp_gt_u32_e64 s[94:95], 16, v33
	v_sub_u32_e32 v33, v46, v32
	v_cmp_gt_u32_e64 s[96:97], 16, v33
	v_or_b32_e32 v33, 57, v157
	v_sub_u32_e32 v33, v33, v32
	v_writelane_b32 v255, s0, 50
	v_cmp_gt_u32_e64 s[98:99], 16, v33
	v_sub_u32_e32 v33, v47, v32
	v_writelane_b32 v255, s1, 51
	v_cmp_gt_u32_e64 s[0:1], 16, v33
	v_or_b32_e32 v33, 58, v157
	v_sub_u32_e32 v33, v33, v32
	v_cmp_gt_u32_e64 s[4:5], 16, v33
	v_sub_u32_e32 v33, v48, v32
	v_cmp_gt_u32_e64 s[6:7], 16, v33
	v_or_b32_e32 v33, 59, v157
	v_sub_u32_e32 v32, v33, v32
	v_cmp_gt_u32_e64 s[8:9], 16, v32
	v_add_u32_e32 v32, s52, v165
	v_sub_u32_e32 v159, v157, v32
	v_add_u32_e32 v32, s18, v157
	s_mul_i32 s18, s55, 0x7c
	s_mulk_i32 s52, 0x7c
	v_sub_u32_e32 v32, v32, v165
	s_sub_i32 s18, s18, s52
	v_max_i32_e32 v32, -15, v32
	s_add_i32 s81, s18, 0
	v_readlane_b32 s18, v254, 51
	v_lshlrev_b32_e32 v178, 2, v32
	v_mov_b64_e32 v[62:63], v[14:15]
	v_add_u32_e32 v32, s18, v157
	v_sub_u32_e32 v32, v32, v165
	v_max_i32_e32 v32, -15, v32
	v_add_u32_e32 v32, 15, v32
	v_min_u32_e32 v32, 30, v32
	v_readlane_b32 s18, v254, 52
	v_lshlrev_b32_e32 v179, 2, v32
	v_mov_b64_e32 v[60:61], v[12:13]
	v_add_u32_e32 v32, s18, v157
	v_sub_u32_e32 v32, v32, v165
	v_max_i32_e32 v32, -15, v32
	v_readlane_b32 s18, v254, 53
	v_lshlrev_b32_e32 v180, 2, v32
	v_mov_b64_e32 v[58:59], v[10:11]
	v_add_u32_e32 v32, s18, v157
	v_sub_u32_e32 v32, v32, v165
	v_max_i32_e32 v32, -15, v32
	v_add_u32_e32 v32, 15, v32
	v_min_u32_e32 v32, 30, v32
	v_readlane_b32 s18, v254, 54
	v_lshlrev_b32_e32 v182, 2, v32
	v_mov_b64_e32 v[56:57], v[8:9]
	v_add_u32_e32 v32, s18, v157
	v_sub_u32_e32 v32, v32, v165
	v_max_i32_e32 v32, -15, v32
	v_readlane_b32 s18, v254, 55
	v_lshlrev_b32_e32 v183, 2, v32
	v_mov_b64_e32 v[54:55], v[6:7]
	v_add_u32_e32 v32, s18, v157
	v_sub_u32_e32 v32, v32, v165
	v_max_i32_e32 v32, -15, v32
	v_add_u32_e32 v32, 15, v32
	v_min_u32_e32 v32, 30, v32
	v_readlane_b32 s18, v254, 56
	v_lshlrev_b32_e32 v184, 2, v32
	v_mov_b64_e32 v[52:53], v[4:5]
	v_add_u32_e32 v32, s18, v157
	v_sub_u32_e32 v32, v32, v165
	v_max_i32_e32 v32, -15, v32
	v_readlane_b32 s18, v254, 57
	v_lshlrev_b32_e32 v185, 2, v32
	v_mov_b64_e32 v[50:51], v[2:3]
	v_add_u32_e32 v32, s18, v157
	v_sub_u32_e32 v32, v32, v165
	v_max_i32_e32 v32, -15, v32
	v_add_u32_e32 v32, 15, v32
	v_min_u32_e32 v32, 30, v32
	v_readlane_b32 s18, v254, 58
	v_lshlrev_b32_e32 v186, 2, v32
	v_mov_b64_e32 v[48:49], v[0:1]
	v_add_u32_e32 v32, s18, v157
	v_sub_u32_e32 v32, v32, v165
	v_max_i32_e32 v32, -15, v32
	v_readlane_b32 s18, v254, 59
	v_lshlrev_b32_e32 v187, 2, v32
	s_nop 0
	v_add_u32_e32 v32, s18, v157
	v_sub_u32_e32 v32, v32, v165
	v_max_i32_e32 v32, -15, v32
	v_add_u32_e32 v32, 15, v32
	v_min_u32_e32 v32, 30, v32
	v_readlane_b32 s18, v254, 60
	v_lshlrev_b32_e32 v188, 2, v32
	s_nop 0
	v_add_u32_e32 v32, s18, v157
	v_sub_u32_e32 v32, v32, v165
	v_max_i32_e32 v32, -15, v32
	v_readlane_b32 s18, v254, 61
	v_lshlrev_b32_e32 v189, 2, v32
	s_nop 0
	v_add_u32_e32 v32, s18, v157
	v_sub_u32_e32 v32, v32, v165
	v_max_i32_e32 v32, -15, v32
; template <int DQ>
; __device__ __forceinline__ void attn_unit(LAS unsigned char* lds, const AttnDesc& A, int tid_in, int wid, int lane_in) {
;     ...
;     f32x16 o0, o1;
; #pragma unroll
;     for (int r = 0; r < 16; ++r) { o0[r] = 0.f; o1[r] = 0.f; }
;     ...
;                 for (int r = 0; r < 16; ++r) {
;                     const int kc = (r & 3) + 8 * (r >> 2) + 4 * h;
;                     { const int dc = min(max(kc - qc + 15, 0), 30); const bool ok = (unsigned)(kc - w0) < 16u; const float bv = rpbl[rbase + dc]; s0[r] = ok ? s0[r] + bv : -1e30f; }
;                     { const int kc2 = kc + 32; const int dc = min(max(kc2 - qc + 15, 0), 30); const bool ok = (unsigned)(kc2 - w0) < 16u; const float bv = rpbl[rbase + dc]; s1[r] = ok ? s1[r] + bv : -1e30f; }
;                 }
	v_add_u32_e32 v32, 15, v32
	v_min_u32_e32 v32, 30, v32
	v_readlane_b32 s18, v254, 62
	v_lshlrev_b32_e32 v190, 2, v32
	s_nop 0
	v_add_u32_e32 v32, s18, v157
	v_sub_u32_e32 v32, v32, v165
	v_max_i32_e32 v32, -15, v32
	v_readlane_b32 s18, v254, 63
	v_lshlrev_b32_e32 v191, 2, v32
	s_nop 0
	v_add_u32_e32 v32, s18, v157
	v_sub_u32_e32 v32, v32, v165
	v_max_i32_e32 v32, -15, v32
	v_add_u32_e32 v32, 15, v32
	v_min_u32_e32 v32, 30, v32
	v_readlane_b32 s18, v255, 0
	v_lshlrev_b32_e32 v192, 2, v32
	s_nop 0
	v_add_u32_e32 v32, s18, v157
	v_sub_u32_e32 v32, v32, v165
	v_max_i32_e32 v32, -15, v32
	v_readlane_b32 s18, v255, 1
	v_lshlrev_b32_e32 v193, 2, v32
	s_nop 0
	v_add_u32_e32 v32, s18, v157
	v_sub_u32_e32 v32, v32, v165
	v_max_i32_e32 v32, -15, v32
	v_add_u32_e32 v32, 15, v32
	v_min_u32_e32 v32, 30, v32
	v_readlane_b32 s18, v255, 2
	v_lshlrev_b32_e32 v194, 2, v32
	s_nop 0
	v_add_u32_e32 v32, s18, v157
	v_sub_u32_e32 v32, v32, v165
	v_max_i32_e32 v32, -15, v32
	v_add_u32_e32 v32, 15, v32
	v_min_u32_e32 v32, 30, v32
	v_readlane_b32 s18, v255, 3
	v_lshlrev_b32_e32 v195, 2, v32
	s_nop 0
	v_add_u32_e32 v32, s18, v157
	v_sub_u32_e32 v32, v32, v165
	v_min_u32_e32 v32, 30, v32
	v_readlane_b32 s18, v255, 4
	v_lshlrev_b32_e32 v196, 2, v32
	s_nop 0
	v_add_u32_e32 v32, s18, v157
	v_sub_u32_e32 v32, v32, v165
	v_max_i32_e32 v32, -15, v32
	v_add_u32_e32 v32, 15, v32
	v_min_u32_e32 v32, 30, v32
	v_readlane_b32 s18, v255, 5
	v_lshlrev_b32_e32 v197, 2, v32
	s_nop 0
	v_add_u32_e32 v32, s18, v157
	v_sub_u32_e32 v32, v32, v165
	v_min_u32_e32 v32, 30, v32
	v_readlane_b32 s18, v255, 6
	v_lshlrev_b32_e32 v198, 2, v32
	s_nop 0
	v_add_u32_e32 v32, s18, v157
	v_sub_u32_e32 v32, v32, v165
	v_max_i32_e32 v32, -15, v32
	v_add_u32_e32 v32, 15, v32
	v_min_u32_e32 v32, 30, v32
	v_readlane_b32 s18, v255, 7
	v_lshlrev_b32_e32 v199, 2, v32
	s_nop 0
	v_add_u32_e32 v32, s18, v157
	v_sub_u32_e32 v32, v32, v165
	v_min_u32_e32 v32, 30, v32
	v_readlane_b32 s18, v255, 8
	v_lshlrev_b32_e32 v200, 2, v32
	s_nop 0
	v_add_u32_e32 v32, s18, v157
	v_sub_u32_e32 v32, v32, v165
	v_max_i32_e32 v32, -15, v32
	v_add_u32_e32 v32, 15, v32
	v_min_u32_e32 v32, 30, v32
	v_readlane_b32 s18, v255, 9
	v_lshlrev_b32_e32 v201, 2, v32
	s_nop 0
	v_add_u32_e32 v32, s18, v157
	v_sub_u32_e32 v32, v32, v165
	v_min_u32_e32 v32, 30, v32
	v_lshlrev_b32_e32 v202, 2, v32
	v_add_u32_e32 v32, s21, v157
	v_sub_u32_e32 v32, v32, v165
	v_max_i32_e32 v32, -15, v32
	v_add_u32_e32 v32, 15, v32
	v_min_u32_e32 v32, 30, v32
	v_lshlrev_b32_e32 v203, 2, v32
	v_add_u32_e32 v32, s23, v157
	v_sub_u32_e32 v32, v32, v165
	v_min_u32_e32 v32, 30, v32
	v_lshlrev_b32_e32 v204, 2, v32
	v_add_u32_e32 v32, s24, v157
	v_sub_u32_e32 v32, v32, v165
	v_max_i32_e32 v32, -15, v32
	v_add_u32_e32 v32, 15, v32
	v_min_u32_e32 v32, 30, v32
	v_lshlrev_b32_e32 v205, 2, v32
	v_add_u32_e32 v32, s25, v157
	v_sub_u32_e32 v32, v32, v165
	v_min_u32_e32 v32, 30, v32
	v_lshlrev_b32_e32 v206, 2, v32
	v_add_u32_e32 v32, s26, v157
	v_sub_u32_e32 v32, v32, v165
	v_max_i32_e32 v32, -15, v32
	v_add_u32_e32 v32, 15, v32
	v_min_u32_e32 v32, 30, v32
	v_lshlrev_b32_e32 v207, 2, v32
	v_add_u32_e32 v32, s27, v157
	v_sub_u32_e32 v32, v32, v165
	v_min_u32_e32 v32, 30, v32
	v_lshlrev_b32_e32 v208, 2, v32
	v_add_u32_e32 v32, s31, v157
	v_sub_u32_e32 v32, v32, v165
	v_max_i32_e32 v32, -15, v32
	v_add_u32_e32 v32, 15, v32
	v_min_u32_e32 v32, 30, v32
	v_lshlrev_b32_e32 v209, 2, v32
	v_add_u32_e32 v32, s46, v157
	v_sub_u32_e32 v32, v32, v165
	v_min_u32_e32 v32, 30, v32
	v_lshlrev_b32_e32 v210, 2, v32
	v_mov_b64_e32 v[46:47], v[14:15]
	v_mov_b64_e32 v[44:45], v[12:13]
	v_mov_b64_e32 v[42:43], v[10:11]
	v_mov_b64_e32 v[40:41], v[8:9]
	v_mov_b64_e32 v[38:39], v[6:7]
	v_mov_b64_e32 v[36:37], v[4:5]
	v_mov_b64_e32 v[34:35], v[2:3]
	v_mov_b64_e32 v[32:33], v[0:1]

; template <int DQ>
; __device__ __forceinline__ void attn_unit(LAS unsigned char* lds, const AttnDesc& A, int tid_in, int wid, int lane_in) {
;     ...
;                 s0 = __builtin_amdgcn_mfma_f32_32x32x16_bf16(kq[s & 1][0], qf[s], s == 0 ? zero16 : s0, 0, 0, 0);
;                 s1 = __builtin_amdgcn_mfma_f32_32x32x16_bf16(kq[s & 1][1], qf[s], s == 0 ? zero16 : s1, 0, 0, 0);
;     ...
;             float mxa = fmaxf(fmaxf(s0[0], s0[1]), s0[2]), mxb = fmaxf(fmaxf(s1[0], s1[1]), s1[2]);
;             mxa = fmaxf(fmaxf(mxa, s0[3]), s0[4]); mxb = fmaxf(fmaxf(mxb, s1[3]), s1[4]);
;             mxa = fmaxf(fmaxf(mxa, s0[5]), s0[6]); mxb = fmaxf(fmaxf(mxb, s1[5]), s1[6]);
;             mxa = fmaxf(fmaxf(mxa, s0[7]), s0[8]); mxb = fmaxf(fmaxf(mxb, s1[7]), s1[8]);
;             mxa = fmaxf(fmaxf(mxa, s0[9]), s0[10]); mxb = fmaxf(fmaxf(mxb, s1[9]), s1[10]);
;             mxa = fmaxf(fmaxf(mxa, s0[11]), s0[12]); mxb = fmaxf(fmaxf(mxb, s1[11]), s1[12]);
;             mxa = fmaxf(fmaxf(mxa, s0[13]), s0[14]); mxb = fmaxf(fmaxf(mxb, s1[13]), s1[14]);
;             float mx = fmaxf(fmaxf(mxa, mxb), fmaxf(s0[15], s1[15]));
;             mx = fmaxf(mx, __shfl_xor(mx, 32));
;             if (__builtin_amdgcn_ballot_w64(mx > mrun + 8.0f) != 0ull) {
;                 const float mnew = fmaxf(mrun, mx);
;                 const float alpha = __builtin_amdgcn_exp2f(mrun - mnew);
;                 mrun = mnew; lrun *= alpha;
; #pragma unroll
;                 for (int r = 0; r < 16; ++r) { o0[r] *= alpha; o1[r] *= alpha; }
;             }
;             float rsa = 0.f, rsb = 0.f;
; #pragma unroll
;             for (int r = 0; r < 16; ++r) { s0[r] = __builtin_amdgcn_exp2f(s0[r] - mrun); s1[r] = __builtin_amdgcn_exp2f(s1[r] - mrun); rsa += s0[r]; rsb += s1[r]; }
;             lrun += rsa + rsb;
.LBB0_132:
	v_max3_f32 v0, v66, v67, v68
	v_max3_f32 v2, v82, v83, v84
	v_max3_f32 v0, v0, v69, v70
	v_max3_f32 v2, v2, v85, v86
	v_max3_f32 v0, v0, v71, v72
	v_max3_f32 v2, v2, v87, v88
	v_max3_f32 v0, v0, v73, v74
	v_max3_f32 v2, v2, v89, v90
	v_max3_f32 v0, v0, v75, v76
	v_max3_f32 v2, v2, v91, v92
	v_max3_f32 v0, v0, v77, v78
	v_max3_f32 v2, v2, v93, v94
	v_max_f32_e32 v3, v97, v97
	v_max_f32_e32 v4, v81, v81
	v_max3_f32 v0, v0, v79, v80
	v_max3_f32 v2, v2, v95, v96
	v_max_f32_e32 v3, v4, v3
	v_max3_f32 v0, v0, v2, v3
	v_and_b32_e32 v3, 64, v242
	v_xor_b32_e32 v2, 32, v242
	v_add_u32_e32 v3, 64, v3
	v_cmp_lt_i32_e32 vcc, v2, v3
	s_nop 1
	v_cndmask_b32_e32 v2, v242, v2, vcc
	v_lshlrev_b32_e32 v2, 2, v2
	ds_bpermute_b32 v2, v2, v0
	s_waitcnt lgkmcnt(0)
	v_max_f32_e32 v2, v2, v2
	v_max_f32_e32 v0, v0, v2
	v_cmp_gt_f32_e32 vcc, v0, v213
	s_cbranch_vccz .LBB0_134
	v_sub_f32_e32 v0, v0, v16
	v_max_f32_e32 v0, v0, v0
	v_max_f32_e32 v2, v212, v212
	v_max_f32_e32 v2, v2, v0
	v_sub_f32_e32 v0, v212, v2
	v_exp_f32_e32 v0, v0
	v_mov_b32_e32 v212, v2
	v_add_f32_e32 v3, v2, v16
	v_cmp_lt_f32_e32 vcc, 0xefa18f08, v2
	v_mov_b32_e32 v5, 0x41000000
	v_pk_mul_f32 v[62:63], v[62:63], v[0:1] op_sel_hi:[1,0]
	v_pk_mul_f32 v[60:61], v[60:61], v[0:1] op_sel_hi:[1,0]
	v_pk_mul_f32 v[58:59], v[58:59], v[0:1] op_sel_hi:[1,0]
	v_pk_mul_f32 v[56:57], v[56:57], v[0:1] op_sel_hi:[1,0]
	v_pk_mul_f32 v[54:55], v[54:55], v[0:1] op_sel_hi:[1,0]
	v_pk_mul_f32 v[52:53], v[52:53], v[0:1] op_sel_hi:[1,0]
	v_pk_mul_f32 v[50:51], v[50:51], v[0:1] op_sel_hi:[1,0]
	v_pk_mul_f32 v[48:49], v[48:49], v[0:1] op_sel_hi:[1,0]
	v_pk_mul_f32 v[46:47], v[46:47], v[0:1] op_sel_hi:[1,0]
	v_pk_mul_f32 v[44:45], v[44:45], v[0:1] op_sel_hi:[1,0]
	v_pk_mul_f32 v[42:43], v[42:43], v[0:1] op_sel_hi:[1,0]
	v_pk_mul_f32 v[40:41], v[40:41], v[0:1] op_sel_hi:[1,0]
	v_pk_mul_f32 v[38:39], v[38:39], v[0:1] op_sel_hi:[1,0]
	v_pk_mul_f32 v[36:37], v[36:37], v[0:1] op_sel_hi:[1,0]
	v_pk_mul_f32 v[34:35], v[34:35], v[0:1] op_sel_hi:[1,0]
	v_pk_mul_f32 v[32:33], v[32:33], v[0:1] op_sel_hi:[1,0]
	v_mul_f32_e32 v64, v64, v0
	v_cndmask_b32_e32 v4, 0, v2, vcc
	v_cndmask_b32_e32 v213, v241, v5, vcc
	v_sub_f32_e32 v66, v66, v3
	v_sub_f32_e32 v67, v67, v3
	v_sub_f32_e32 v68, v68, v3
	v_sub_f32_e32 v69, v69, v3
	v_sub_f32_e32 v70, v70, v3
	v_sub_f32_e32 v71, v71, v3
	v_sub_f32_e32 v72, v72, v3
	v_sub_f32_e32 v73, v73, v3
	v_sub_f32_e32 v74, v74, v3
	v_sub_f32_e32 v75, v75, v3
	v_sub_f32_e32 v76, v76, v3
	v_sub_f32_e32 v77, v77, v3
	v_sub_f32_e32 v78, v78, v3
	v_sub_f32_e32 v79, v79, v3
	v_sub_f32_e32 v80, v80, v3
	v_sub_f32_e32 v81, v81, v3
	v_sub_f32_e32 v82, v82, v3
	v_sub_f32_e32 v83, v83, v3
	v_sub_f32_e32 v84, v84, v3
	v_sub_f32_e32 v85, v85, v3
	v_sub_f32_e32 v86, v86, v3
	v_sub_f32_e32 v87, v87, v3
	v_sub_f32_e32 v88, v88, v3
	v_sub_f32_e32 v89, v89, v3
	v_sub_f32_e32 v90, v90, v3
	v_sub_f32_e32 v91, v91, v3
	v_sub_f32_e32 v92, v92, v3
	v_sub_f32_e32 v93, v93, v3
	v_sub_f32_e32 v94, v94, v3
	v_sub_f32_e32 v95, v95, v3
	v_sub_f32_e32 v96, v96, v3
	v_sub_f32_e32 v97, v97, v3
	v_sub_f32_e32 v16, 0, v4
	v_sub_f32_e32 v17, 0, v4
	v_sub_f32_e32 v18, 0, v4
	v_sub_f32_e32 v19, 0, v4
	v_sub_f32_e32 v20, 0, v4
	v_sub_f32_e32 v21, 0, v4
	v_sub_f32_e32 v22, 0, v4
	v_sub_f32_e32 v23, 0, v4
	v_sub_f32_e32 v24, 0, v4
	v_sub_f32_e32 v25, 0, v4
	v_sub_f32_e32 v26, 0, v4
	v_sub_f32_e32 v27, 0, v4
	v_sub_f32_e32 v28, 0, v4
	v_sub_f32_e32 v29, 0, v4
	v_sub_f32_e32 v30, 0, v4
	v_sub_f32_e32 v31, 0, v4
.LBB0_134:
	v_exp_f32_e32 v3, v66
	v_exp_f32_e32 v2, v82
	v_exp_f32_e32 v5, v67
	v_exp_f32_e32 v4, v83
	v_exp_f32_e32 v9, v68
	v_exp_f32_e32 v8, v84
	v_exp_f32_e32 v11, v69
	v_exp_f32_e32 v10, v85
	v_exp_f32_e32 v15, v70
	v_exp_f32_e32 v14, v86
	v_exp_f32_e32 v71, v71
	v_exp_f32_e32 v70, v87
	v_exp_f32_e32 v83, v72
	v_exp_f32_e32 v82, v88
	v_exp_f32_e32 v73, v73
	v_exp_f32_e32 v72, v89
	v_exp_f32_e32 v85, v74
	v_exp_f32_e32 v84, v90
	v_exp_f32_e32 v75, v75
	v_exp_f32_e32 v74, v91
	v_exp_f32_e32 v87, v76
	v_cvt_pk_bf16_f32 v66, v3, v5
	v_cvt_pk_bf16_f32 v6, v2, v4
	v_pk_add_f32 v[2:3], v[2:3], 0 op_sel_hi:[1,0]
	v_exp_f32_e32 v86, v92
	v_pk_add_f32 v[2:3], v[4:5], v[2:3]
	v_exp_f32_e32 v77, v77
	v_pk_add_f32 v[2:3], v[8:9], v[2:3]
	v_exp_f32_e32 v76, v93
	v_pk_add_f32 v[92:93], v[10:11], v[2:3]
	v_exp_f32_e32 v89, v78
	v_cvt_pk_bf16_f32 v7, v8, v10
	v_cvt_pk_bf16_f32 v68, v15, v71
	v_cvt_pk_bf16_f32 v8, v14, v70
	v_pk_add_f32 v[14:15], v[14:15], v[92:93]
	v_exp_f32_e32 v88, v94
	v_pk_add_f32 v[14:15], v[70:71], v[14:15]
	v_exp_f32_e32 v79, v79
	v_pk_add_f32 v[14:15], v[82:83], v[14:15]
	v_exp_f32_e32 v78, v95
	v_pk_add_f32 v[14:15], v[72:73], v[14:15]
	v_exp_f32_e32 v91, v80
	v_pk_add_f32 v[14:15], v[84:85], v[14:15]
	v_exp_f32_e32 v90, v96
	v_pk_add_f32 v[14:15], v[74:75], v[14:15]
	v_exp_f32_e32 v81, v81
	v_pk_add_f32 v[14:15], v[86:87], v[14:15]
	v_exp_f32_e32 v80, v97
	v_pk_add_f32 v[14:15], v[76:77], v[14:15]
	v_cvt_pk_bf16_f32 v67, v9, v11
	v_pk_add_f32 v[14:15], v[88:89], v[14:15]
	v_cvt_pk_bf16_f32 v69, v83, v73
	v_pk_add_f32 v[14:15], v[78:79], v[14:15]
	v_cvt_pk_bf16_f32 v9, v82, v72
	v_pk_add_f32 v[14:15], v[90:91], v[14:15]
	v_cvt_pk_bf16_f32 v10, v85, v75
	v_pk_add_f32 v[14:15], v[80:81], v[14:15]
	v_cvt_pk_bf16_f32 v11, v87, v77
	v_add_f32_e32 v0, v14, v15
	v_add_u32_e32 v14, s18, v65
	v_add3_u32 v14, v14, v171, v172
	v_cvt_pk_bf16_f32 v12, v89, v79
	v_cvt_pk_bf16_f32 v13, v91, v81
	v_cvt_pk_bf16_f32 v2, v84, v74
	v_cvt_pk_bf16_f32 v3, v86, v76
	v_cvt_pk_bf16_f32 v4, v88, v78
	v_cvt_pk_bf16_f32 v5, v90, v80
	ds_read_b64_tr_b16 v[70:71], v14 offset:26624
	ds_read_b64_tr_b16 v[72:73], v14 offset:27136
	ds_read_b64_tr_b16 v[74:75], v14 offset:30720
	ds_read_b64_tr_b16 v[76:77], v14 offset:31232
	ds_read_b64_tr_b16 v[78:79], v14 offset:27648
	ds_read_b64_tr_b16 v[80:81], v14 offset:28160
	ds_read_b64_tr_b16 v[82:83], v14 offset:31744
	ds_read_b64_tr_b16 v[84:85], v14 offset:32256
	s_waitcnt lgkmcnt(0)
	v_mfma_f32_32x32x16_bf16 v[48:63], v[70:73], v[66:69], v[48:63]
	v_add_f32_e32 v64, v64, v0
	v_mfma_f32_32x32x16_bf16 v[32:47], v[74:77], v[66:69], v[32:47]
	ds_read_b64_tr_b16 v[66:67], v14 offset:28672
	ds_read_b64_tr_b16 v[68:69], v14 offset:29184
	ds_read_b64_tr_b16 v[70:71], v14 offset:32768
	ds_read_b64_tr_b16 v[72:73], v14 offset:33280
	v_mfma_f32_32x32x16_bf16 v[48:63], v[78:81], v[10:13], v[48:63]
	v_mfma_f32_32x32x16_bf16 v[32:47], v[82:85], v[10:13], v[32:47]
	ds_read_b64_tr_b16 v[10:11], v14 offset:29696
	ds_read_b64_tr_b16 v[12:13], v14 offset:30208
	ds_read_b64_tr_b16 v[74:75], v14 offset:33792
	ds_read_b64_tr_b16 v[76:77], v14 offset:34304
	s_waitcnt lgkmcnt(0)
	v_mfma_f32_32x32x16_bf16 v[48:63], v[66:69], v[6:9], v[48:63]
	v_mfma_f32_32x32x16_bf16 v[32:47], v[70:73], v[6:9], v[32:47]
	v_mfma_f32_32x32x16_bf16 v[48:63], v[10:13], v[2:5], v[48:63]
	v_mfma_f32_32x32x16_bf16 v[32:47], v[74:77], v[2:5], v[32:47]

; template <int DQ>
; __device__ __forceinline__ void attn_unit(LAS unsigned char* lds, const AttnDesc& A, int tid_in, int wid, int lane_in) {
;     ...
;     f32x16 o0, o1;
; #pragma unroll
;     for (int r = 0; r < 16; ++r) { o0[r] = 0.f; o1[r] = 0.f; }
;     float mrun = -1e30f, lrun = 0.f;
;     f32x16 zero16;
; #pragma unroll
;     for (int r = 0; r < 16; ++r) zero16[r] = 0.f;
;     asm volatile("" : "+v"(zero16));
.LBB0_137:
	v_mov_b32_e32 v64, 0
	v_mov_b32_e32 v65, v64
	v_mov_b32_e32 v66, v64
	v_mov_b32_e32 v67, v64
	v_mov_b32_e32 v68, v64
	v_mov_b32_e32 v69, v64
	v_mov_b32_e32 v70, v64
	v_mov_b32_e32 v71, v64
	v_mov_b32_e32 v72, v64
	v_mov_b32_e32 v73, v64
	v_mov_b32_e32 v74, v64
	v_mov_b32_e32 v75, v64
	v_mov_b32_e32 v76, v64
	v_mov_b32_e32 v77, v64
	v_mov_b32_e32 v78, v64
	v_mov_b32_e32 v79, v64
	v_mov_b64_e32 v[48:49], v[64:65]
	v_mov_b64_e32 v[32:33], v[64:65]
	v_mov_b32_e32 v212, 0xf149f2ca
	v_mov_b32_e32 v213, 0xf149f2ca
	v_mov_b64_e32 v[50:51], v[66:67]
	v_mov_b64_e32 v[52:53], v[68:69]
	v_mov_b64_e32 v[54:55], v[70:71]
	v_mov_b64_e32 v[56:57], v[72:73]
	v_mov_b64_e32 v[58:59], v[74:75]
	v_mov_b64_e32 v[60:61], v[76:77]
	v_mov_b64_e32 v[62:63], v[78:79]
	v_mov_b64_e32 v[34:35], v[66:67]
	v_mov_b64_e32 v[36:37], v[68:69]
	v_mov_b64_e32 v[38:39], v[70:71]
	v_mov_b64_e32 v[40:41], v[72:73]
	v_mov_b64_e32 v[42:43], v[74:75]
	v_mov_b64_e32 v[44:45], v[76:77]
	v_mov_b64_e32 v[46:47], v[78:79]
	s_branch .LBB0_139

; #define MLA_PACK(S, q) __builtin_bit_cast(bf16x8, (u32x4){cvt_pk_bf16_m(S[8 * (q) + 0], S[8 * (q) + 1]), cvt_pk_bf16_m(S[8 * (q) + 2], S[8 * (q) + 3]), cvt_pk_bf16_m(S[8 * (q) + 4], S[8 * (q) + 5]), cvt_pk_bf16_m(S[8 * (q) + 6], S[8 * (q) + 7])})
; #define MLA_MM(PF, VA, VC) do { o0 = __builtin_amdgcn_mfma_f32_32x32x16_bf16(VA, PF, o0, 0, 0, 0); o1 = __builtin_amdgcn_mfma_f32_32x32x16_bf16(VC, PF, o1, 0, 0, 0); } while (0)
; __device__ __forceinline__ void attn_unit_mla(LAS unsigned char* lds, const AttnDesc& A, int tid_in, int wid, int lane_in) {
;     ...
;     float mrun = -1e30f, lrun = 0.f;
;     const int skey = tid >> 3, sch = tid & 7;
;     u32x4 ka, va, kra = (u32x4){0u, 0u, 0u, 0u}, kb_, vb_, krb = (u32x4){0u, 0u, 0u, 0u};
;     ...
;         float ra = 0.f, rb = 0.f;
; #pragma unroll
;         for (int r = 0; r < 16; ++r) { s0[r] = __builtin_amdgcn_exp2f(s0[r] - mrun); s1[r] = __builtin_amdgcn_exp2f(s1[r] - mrun); s2[r] = __builtin_amdgcn_exp2f(s2[r] - mrun); s3[r] = __builtin_amdgcn_exp2f(s3[r] - mrun);
;             ra += s0[r] + s1[r]; rb += s2[r] + s3[r]; }
;         lrun += ra + rb;
;     ...
;         __builtin_amdgcn_s_setprio(1);
;     ...
;         { bf16x8 va1, vc1;
;           { const bf16x8 p = MLA_PACK(s0, 0); MLA_VRD(va1, vc1, vbuf, 1); MLA_MM(p, va0, vc0); }
;           { const bf16x8 p = MLA_PACK(s0, 1); MLA_VRD(va0, vc0, vbuf, 2); MLA_MM(p, va1, vc1); }
;           { const bf16x8 p = MLA_PACK(s1, 0); MLA_VRD(va1, vc1, vbuf, 3); MLA_MM(p, va0, vc0); }
.LBB0_151:
	s_or_b64 exec, exec, s[8:9]
	v_and_b32_e32 v3, 0xc0, v8
	v_and_b32_e32 v8, 16, v6
	v_lshlrev_b32_e32 v6, 2, v6
	v_and_or_b32 v6, v6, 12, v8
	v_lshlrev_b32_e32 v6, 1, v6
	v_lshlrev_b32_e32 v8, 8, v157
	v_or3_b32 v161, v6, v3, v8
	v_lshlrev_b32_e32 v3, 10, v7
	v_and_b32_e32 v6, 64, v242
	v_and_b32_e32 v175, 0x1000, v3
	v_xor_b32_e32 v3, 32, v242
	v_add_u32_e32 v6, 64, v6
	v_cmp_lt_i32_e32 vcc, v3, v6
	s_lshr_b32 s18, s41, 1
	v_mov_b32_e32 v16, v1
	v_cndmask_b32_e32 v3, v242, v3, vcc
	v_lshlrev_b32_e32 v174, 2, v3
	v_mov_b32_e32 v3, v1
	v_mov_b32_e32 v17, v1
	s_movk_i32 s19, 0xd0
	v_lshl_add_u64 v[162:163], s[6:7], 0, v[2:3]
	v_lshl_add_u64 v[164:165], v[4:5], 1, s[92:93]
	s_lshl_b32 s49, s18, 7
	v_mov_b32_e32 v2, v1
	v_mov_b32_e32 v4, v1
	v_mov_b32_e32 v5, v1
	v_mov_b32_e32 v6, v1
	v_mov_b32_e32 v7, v1
	v_mov_b32_e32 v8, v1
	v_mov_b32_e32 v9, v1
	v_mov_b32_e32 v10, v1
	v_mov_b32_e32 v11, v1
	v_mov_b32_e32 v12, v1
	v_mov_b32_e32 v13, v1
	v_mov_b32_e32 v14, v1
	v_mov_b32_e32 v15, v1
	v_mov_b64_e32 v[32:33], v[16:17]
	s_ashr_i32 s5, s4, 31
	s_mov_b32 s8, 1
	s_or_b32 s9, s18, 2
	v_mul_lo_u32 v172, v171, s19
	v_mul_lo_u32 v173, v159, s19
	v_lshlrev_b32_e32 v176, 6, v171
	v_mul_u32_u24_e32 v177, 0xd0, v156
	s_mov_b32 s48, 0
	s_addk_i32 s49, 0x100
	v_mov_b32_e32 v179, 0xf149f2ca
	v_mov_b32_e32 v222, 0xf149f2ca
	v_mov_b32_e32 v206, 0
	v_mov_b32_e32 v207, 0
	v_mov_b32_e32 v208, 0
	v_mov_b32_e32 v209, 0
	v_mov_b32_e32 v210, 0
	v_mov_b32_e32 v211, 0
	v_mov_b32_e32 v212, 0
	v_mov_b32_e32 v213, 0
	v_mov_b32_e32 v214, 0
	v_mov_b32_e32 v215, 0
	v_mov_b32_e32 v216, 0
	v_mov_b32_e32 v217, 0
	v_mov_b32_e32 v218, 0
	v_mov_b32_e32 v219, 0
	v_mov_b32_e32 v220, 0
	v_mov_b32_e32 v221, 0
	v_mov_b32_e32 v178, 0
	s_mov_b32 s50, 3
	v_mov_b64_e32 v[30:31], v[14:15]
	v_mov_b64_e32 v[28:29], v[12:13]
	v_mov_b64_e32 v[26:27], v[10:11]
	v_mov_b64_e32 v[24:25], v[8:9]
	v_mov_b64_e32 v[22:23], v[6:7]
	v_mov_b64_e32 v[20:21], v[4:5]
	v_mov_b64_e32 v[18:19], v[2:3]
	s_branch .LBB0_153
.LBB0_152:
	v_exp_f32_e32 v188, v66
	v_exp_f32_e32 v183, v82
	v_exp_f32_e32 v189, v50
	v_exp_f32_e32 v182, v34
	v_exp_f32_e32 v190, v83
	v_exp_f32_e32 v192, v51
	v_exp_f32_e32 v191, v67
	v_exp_f32_e32 v194, v84
	v_exp_f32_e32 v193, v35
	v_exp_f32_e32 v195, v68
	v_exp_f32_e32 v196, v52
	v_exp_f32_e32 v197, v36
	v_add_f32_e32 v34, v188, v183
	v_add_f32_e32 v50, v182, v189
	v_add_f32_e32 v34, 0, v34
	v_add_f32_e32 v35, 0, v50
	v_add_f32_e32 v50, v191, v190
	v_add_f32_e32 v34, v50, v34
	v_add_f32_e32 v50, v193, v192
	v_add_f32_e32 v36, v195, v194
	v_add_f32_e32 v35, v50, v35
	v_add_f32_e32 v34, v36, v34
	v_add_f32_e32 v36, v197, v196
	v_add_f32_e32 v35, v36, v35
	v_exp_f32_e32 v198, v85
	v_exp_f32_e32 v199, v69
	v_exp_f32_e32 v200, v53
	v_exp_f32_e32 v201, v37
	v_add_f32_e32 v36, v199, v198
	v_add_f32_e32 v185, v36, v34
	v_exp_f32_e32 v202, v86
	v_exp_f32_e32 v203, v70
	v_exp_f32_e32 v204, v54
	v_exp_f32_e32 v205, v38
	v_add_f32_e32 v34, v201, v200
	v_add_f32_e32 v184, v34, v35
	v_exp_f32_e32 v83, v87
	v_exp_f32_e32 v51, v71
	v_exp_f32_e32 v82, v55
	v_exp_f32_e32 v50, v39
	v_exp_f32_e32 v85, v88
	v_exp_f32_e32 v53, v72
	v_exp_f32_e32 v84, v56
	v_exp_f32_e32 v52, v40
	v_exp_f32_e32 v87, v89
	v_exp_f32_e32 v55, v73
	v_exp_f32_e32 v86, v57
	v_exp_f32_e32 v54, v41
	v_exp_f32_e32 v67, v90
	v_exp_f32_e32 v35, v74
	v_exp_f32_e32 v69, v91
	v_exp_f32_e32 v66, v58
	v_mov_b32_e32 v34, v42
	v_exp_f32_e32 v37, v75
	v_mov_b32_e32 v36, v59
	v_exp_f32_e32 v59, v92
	v_exp_f32_e32 v71, v93
	v_exp_f32_e32 v39, v76
	v_exp_f32_e32 v41, v77
	v_mov_b32_e32 v40, v61
	v_exp_f32_e32 v61, v94
	v_exp_f32_e32 v68, v36
	v_mov_b32_e32 v36, v43
	v_exp_f32_e32 v58, v60
	v_mov_b32_e32 v38, v44
	v_exp_f32_e32 v43, v78
	v_exp_f32_e32 v60, v62
	v_mov_b32_e32 v42, v46
	v_exp_f32_e32 v73, v95
	v_exp_f32_e32 v70, v40
	v_mov_b32_e32 v40, v45
	v_exp_f32_e32 v45, v79
	v_mov_b32_e32 v44, v63
	v_exp_f32_e32 v63, v96
	v_exp_f32_e32 v72, v44
	v_mov_b32_e32 v44, v47
	v_exp_f32_e32 v47, v80
	v_exp_f32_e32 v62, v64
	v_mov_b32_e32 v46, v48
	v_exp_f32_e32 v75, v97
	v_exp_f32_e32 v57, v81
	v_add_f32_e32 v187, v203, v202
	v_add_f32_e32 v186, v205, v204
	v_exp_f32_e32 v34, v34
	v_exp_f32_e32 v74, v65
	v_exp_f32_e32 v36, v36
	v_exp_f32_e32 v56, v49
	v_pk_add_f32 v[48:49], v[186:187], v[184:185]
	v_pk_add_f32 v[64:65], v[50:51], v[82:83]
	v_exp_f32_e32 v38, v38
	v_pk_add_f32 v[48:49], v[64:65], v[48:49]
	v_pk_add_f32 v[64:65], v[52:53], v[84:85]
	v_exp_f32_e32 v40, v40
	v_pk_add_f32 v[48:49], v[64:65], v[48:49]
	v_pk_add_f32 v[64:65], v[54:55], v[86:87]
	v_exp_f32_e32 v42, v42
	v_pk_add_f32 v[48:49], v[64:65], v[48:49]
	v_pk_add_f32 v[64:65], v[34:35], v[66:67]
	v_exp_f32_e32 v44, v44
	v_pk_add_f32 v[48:49], v[64:65], v[48:49]
	v_pk_add_f32 v[64:65], v[36:37], v[68:69]
	v_exp_f32_e32 v46, v46
	v_pk_add_f32 v[48:49], v[64:65], v[48:49]
	v_pk_add_f32 v[64:65], v[38:39], v[58:59]
	s_nop 0
	v_pk_add_f32 v[48:49], v[64:65], v[48:49]
	v_pk_add_f32 v[64:65], v[40:41], v[70:71]
	s_nop 0
	v_pk_add_f32 v[48:49], v[64:65], v[48:49]
	v_pk_add_f32 v[64:65], v[42:43], v[60:61]
	s_nop 0
	v_pk_add_f32 v[48:49], v[64:65], v[48:49]
	v_pk_add_f32 v[64:65], v[44:45], v[72:73]
	s_nop 0
	v_pk_add_f32 v[48:49], v[64:65], v[48:49]
	v_pk_add_f32 v[64:65], v[46:47], v[62:63]
	s_nop 0
	v_pk_add_f32 v[48:49], v[64:65], v[48:49]
	v_pk_add_f32 v[64:65], v[56:57], v[74:75]
	s_nop 0
	v_pk_add_f32 v[48:49], v[64:65], v[48:49]
	s_nop 0
	v_add_f32_e32 v48, v48, v49
	v_add_f32_e32 v178, v178, v48
	s_setprio 1
	v_cvt_pk_bf16_f32 v76, v183, v190
	v_cvt_pk_bf16_f32 v77, v194, v198
	v_cvt_pk_bf16_f32 v78, v202, v83
	v_cvt_pk_bf16_f32 v79, v85, v87
	v_cvt_pk_bf16_f32 v88, v67, v69
	v_cvt_pk_bf16_f32 v89, v59, v71
	v_mfma_f32_32x32x16_bf16 v[2:17], v[150:153], v[76:79], v[2:17]
	v_cvt_pk_bf16_f32 v90, v61, v73
	v_cvt_pk_bf16_f32 v91, v63, v75
	v_cvt_pk_bf16_f32 v68, v66, v68
	v_cvt_pk_bf16_f32 v69, v58, v70
	v_cvt_pk_bf16_f32 v70, v60, v72
	v_cvt_pk_bf16_f32 v71, v62, v74
	v_cvt_pk_bf16_f32 v48, v182, v193
	v_mfma_f32_32x32x16_bf16 v[18:33], v[146:149], v[76:79], v[18:33]
	ds_read_b64_tr_b16 v[76:77], v180 offset:54272
	ds_read_b64_tr_b16 v[78:79], v180 offset:54784
	v_cvt_pk_bf16_f32 v49, v197, v201
	v_cvt_pk_bf16_f32 v50, v205, v50
	v_cvt_pk_bf16_f32 v34, v34, v36
	v_cvt_pk_bf16_f32 v36, v42, v44
	s_waitcnt lgkmcnt(0)
; #define MLA_PACK(S, q) __builtin_bit_cast(bf16x8, (u32x4){cvt_pk_bf16_m(S[8 * (q) + 0], S[8 * (q) + 1]), cvt_pk_bf16_m(S[8 * (q) + 2], S[8 * (q) + 3]), cvt_pk_bf16_m(S[8 * (q) + 4], S[8 * (q) + 5]), cvt_pk_bf16_m(S[8 * (q) + 6], S[8 * (q) + 7])})
; #define MLA_MM(PF, VA, VC) do { o0 = __builtin_amdgcn_mfma_f32_32x32x16_bf16(VA, PF, o0, 0, 0, 0); o1 = __builtin_amdgcn_mfma_f32_32x32x16_bf16(VC, PF, o1, 0, 0, 0); } while (0)
; __device__ __forceinline__ void attn_unit_mla(LAS unsigned char* lds, const AttnDesc& A, int tid_in, int wid, int lane_in) {
;     ...
;         { bf16x8 va1, vc1;
;           { const bf16x8 p = MLA_PACK(s0, 0); MLA_VRD(va1, vc1, vbuf, 1); MLA_MM(p, va0, vc0); }
;           { const bf16x8 p = MLA_PACK(s0, 1); MLA_VRD(va0, vc0, vbuf, 2); MLA_MM(p, va1, vc1); }
;           { const bf16x8 p = MLA_PACK(s1, 0); MLA_VRD(va1, vc1, vbuf, 3); MLA_MM(p, va0, vc0); }
;           { const bf16x8 p = MLA_PACK(s1, 1); MLA_VRD(va0, vc0, vbuf + 8192, 0); MLA_MM(p, va1, vc1); }
;           { const bf16x8 p = MLA_PACK(s2, 0); MLA_VRD(va1, vc1, vbuf + 8192, 1); MLA_MM(p, va0, vc0); }
;           { const bf16x8 p = MLA_PACK(s2, 1); MLA_VRD(va0, vc0, vbuf + 8192, 2); MLA_MM(p, va1, vc1); }
;           { const bf16x8 p = MLA_PACK(s3, 0); MLA_VRD(va1, vc1, vbuf + 8192, 3); MLA_MM(p, va0, vc0); }
;           { const bf16x8 p = MLA_PACK(s3, 1); MLA_MM(p, va1, vc1); } }
;         __builtin_amdgcn_s_setprio(0);
	v_mfma_f32_32x32x16_bf16 v[2:17], v[76:79], v[88:91], v[2:17]
	ds_read_b64_tr_b16 v[76:77], v180 offset:58368
	ds_read_b64_tr_b16 v[78:79], v180 offset:58880
	ds_read_b64_tr_b16 v[92:93], v180 offset:55296
	ds_read_b64_tr_b16 v[94:95], v180 offset:55808
	s_waitcnt lgkmcnt(0)
	v_mfma_f32_32x32x16_bf16 v[18:33], v[76:79], v[88:91], v[18:33]
	v_cvt_pk_bf16_f32 v76, v188, v191
	v_cvt_pk_bf16_f32 v77, v195, v199
	v_cvt_pk_bf16_f32 v78, v203, v51
	v_cvt_pk_bf16_f32 v79, v53, v55
	ds_read_b64_tr_b16 v[88:89], v180 offset:59392
	ds_read_b64_tr_b16 v[90:91], v180 offset:59904
	ds_read_b64_tr_b16 v[80:81], v180 offset:56832
	v_cvt_pk_bf16_f32 v51, v52, v54
	v_mfma_f32_32x32x16_bf16 v[2:17], v[92:95], v[76:79], v[2:17]
	s_waitcnt lgkmcnt(0)
	v_mfma_f32_32x32x16_bf16 v[18:33], v[88:91], v[76:79], v[18:33]
	ds_read_b64_tr_b16 v[78:79], v180 offset:56320
	ds_read_b64_tr_b16 v[76:77], v180 offset:60416
	v_cvt_pk_bf16_f32 v88, v35, v37
	v_cvt_pk_bf16_f32 v89, v39, v41
	v_cvt_pk_bf16_f32 v90, v43, v45
	v_cvt_pk_bf16_f32 v91, v47, v57
	v_add_u32_e32 v39, 0xf000, v180
	v_cvt_pk_bf16_f32 v35, v38, v40
	s_waitcnt lgkmcnt(0)
	v_mfma_f32_32x32x16_bf16 v[2:17], v[78:81], v[88:91], v[2:17]
	ds_read_b64_tr_b16 v[78:79], v180 offset:60928
	ds_read_b64_tr_b16 v[92:93], v180 offset:61440
	ds_read_b64_tr_b16 v[94:95], v180 offset:61952
	v_cvt_pk_bf16_f32 v37, v46, v56
	s_waitcnt lgkmcnt(0)
	v_mfma_f32_32x32x16_bf16 v[18:33], v[76:79], v[88:91], v[18:33]
	v_cvt_pk_bf16_f32 v76, v189, v192
	v_cvt_pk_bf16_f32 v77, v196, v200
	v_cvt_pk_bf16_f32 v78, v204, v82
	v_cvt_pk_bf16_f32 v79, v84, v86
	ds_read_b64_tr_b16 v[80:81], v39 offset:4096
	ds_read_b64_tr_b16 v[82:83], v39 offset:4608
	ds_read_b64_tr_b16 v[84:85], v180 offset:62464
	ds_read_b64_tr_b16 v[86:87], v180 offset:62976
	ds_read_b64_tr_b16 v[64:65], v39 offset:5120
	ds_read_b64_tr_b16 v[66:67], v39 offset:5632
	v_mfma_f32_32x32x16_bf16 v[2:17], v[92:95], v[76:79], v[2:17]
	ds_read_b64_tr_b16 v[58:59], v180 offset:63488
	ds_read_b64_tr_b16 v[60:61], v180 offset:64000
	s_waitcnt lgkmcnt(0)
	v_mfma_f32_32x32x16_bf16 v[18:33], v[80:83], v[76:79], v[18:33]
	v_mfma_f32_32x32x16_bf16 v[2:17], v[84:87], v[68:71], v[2:17]
	v_mfma_f32_32x32x16_bf16 v[18:33], v[64:67], v[68:71], v[18:33]
	v_mfma_f32_32x32x16_bf16 v[2:17], v[58:61], v[48:51], v[2:17]
	ds_read_b64_tr_b16 v[52:53], v39 offset:6144
	ds_read_b64_tr_b16 v[54:55], v39 offset:6656
	ds_read_b64_tr_b16 v[58:59], v180 offset:64512
	s_waitcnt lgkmcnt(0)
	v_mfma_f32_32x32x16_bf16 v[18:33], v[52:55], v[48:51], v[18:33]
	ds_read_b64_tr_b16 v[60:61], v180 offset:65024
	ds_read_b64_tr_b16 v[48:49], v39 offset:7168
	ds_read_b64_tr_b16 v[50:51], v39 offset:7680
	s_waitcnt lgkmcnt(0)
	v_mfma_f32_32x32x16_bf16 v[2:17], v[58:61], v[34:37], v[2:17]
	v_mfma_f32_32x32x16_bf16 v[18:33], v[48:51], v[34:37], v[18:33]
	s_setprio 0
	s_addk_i32 s48, 0x80
	s_add_i32 s50, s50, 2
	s_add_i32 s8, s8, 1
	s_cmp_lg_u32 s49, s48
	s_cbranch_scc0 .LBB0_27

; #define MLA_KRD(SET, st_) do { const int co_ = (16 * (st_) + 8 * h) * 2; \
;             kf[SET][0] = *(const LAS bf16x8*)(kbuf + r32 * KSTR + co_); kf[SET][1] = *(const LAS bf16x8*)(kbuf + (32 + r32) * KSTR + co_); \
;             kf[SET][2] = *(const LAS bf16x8*)(kbuf + ATT_KBUF + r32 * KSTR + co_); kf[SET][3] = *(const LAS bf16x8*)(kbuf + ATT_KBUF + (32 + r32) * KSTR + co_); } while (0)
; __device__ __forceinline__ void attn_unit_mla(LAS unsigned char* lds, const AttnDesc& A, int tid_in, int wid, int lane_in) {
;     ...
;         f32x16 s0, s1, s2, s3;
; #pragma unroll
;         for (int r = 0; r < 16; ++r) { s0[r] = 0.f; s1[r] = 0.f; s2[r] = 0.f; s3[r] = 0.f; }
;         __builtin_amdgcn_s_setprio(1);
;         bf16x8 kf[2][4];
;     ...
;         MLA_KRD(0, 0);
;         __builtin_amdgcn_sched_group_barrier(0x100, 4, 0);
; #pragma unroll
;         for (int s = 0; s < NS; ++s) {
;             if (s + 1 < NS) { MLA_KRD((s + 1) & 1, s + 1); __builtin_amdgcn_sched_group_barrier(0x100, 4, 0); }
;             s0 = __builtin_amdgcn_mfma_f32_32x32x16_bf16(kf[s & 1][0], qf[s], s0, 0, 0, 0);
;             s1 = __builtin_amdgcn_mfma_f32_32x32x16_bf16(kf[s & 1][1], qf[s], s1, 0, 0, 0);
;             s2 = __builtin_amdgcn_mfma_f32_32x32x16_bf16(kf[s & 1][2], qf[s], s2, 0, 0, 0);
;             s3 = __builtin_amdgcn_mfma_f32_32x32x16_bf16(kf[s & 1][3], qf[s], s3, 0, 0, 0);
;             __builtin_amdgcn_sched_group_barrier(0x008, 4, 0);
;         }
;     ...
;         __builtin_amdgcn_s_setprio(0);
;         bf16x8 va0, vc0;
;         MLA_VRD0(va0, vc0, vbuf);
;         float m0 = fmaxf(fmaxf(s0[0], s1[0]), fmaxf(s2[0], s3[0]));
; #pragma unroll
;         for (int r = 1; r < 16; ++r) { m0 = fmaxf(fmaxf(m0, s0[r]), s1[r]); m0 = fmaxf(fmaxf(m0, s2[r]), s3[r]); }
;         float mx = fmaxf(m0, __shfl_xor(m0, 32));
;         if (__builtin_amdgcn_ballot_w64(mx > mrun + 8.0f) != 0ull) {
.LBB0_163:
	s_setprio 1
	v_add3_u32 v180, s52, v177, v0
	ds_read_b128 v[34:37], v180
	ds_read_b128 v[38:41], v180 offset:6656
	ds_read_b128 v[42:45], v180 offset:13312
	ds_read_b128 v[46:49], v180 offset:19968
	ds_read_b128 v[146:149], v180 offset:32
	ds_read_b128 v[150:153], v180 offset:6688
	ds_read_b128 v[182:185], v180 offset:13344
	ds_read_b128 v[186:189], v180 offset:20000
	s_waitcnt lgkmcnt(0)
	v_mfma_f32_32x32x16_bf16 v[82:97], v[34:37], v[98:101], v[206:221]
	v_mfma_f32_32x32x16_bf16 v[66:81], v[38:41], v[98:101], v[206:221]
	v_mfma_f32_32x32x16_bf16 v[50:65], v[42:45], v[98:101], v[206:221]
	v_mfma_f32_32x32x16_bf16 v[34:49], v[46:49], v[98:101], v[206:221]
	ds_read_b128 v[190:193], v180 offset:64
	ds_read_b128 v[194:197], v180 offset:6720
	ds_read_b128 v[198:201], v180 offset:13376
	ds_read_b128 v[202:205], v180 offset:20032
	v_mfma_f32_32x32x16_bf16 v[82:97], v[146:149], v[102:105], v[82:97]
	v_mfma_f32_32x32x16_bf16 v[66:81], v[150:153], v[102:105], v[66:81]
	v_mfma_f32_32x32x16_bf16 v[50:65], v[182:185], v[102:105], v[50:65]
	v_mfma_f32_32x32x16_bf16 v[34:49], v[186:189], v[102:105], v[34:49]
	ds_read_b128 v[146:149], v180 offset:96
	ds_read_b128 v[150:153], v180 offset:6752
	ds_read_b128 v[182:185], v180 offset:13408
	ds_read_b128 v[186:189], v180 offset:20064
	s_waitcnt lgkmcnt(0)
	v_mfma_f32_32x32x16_bf16 v[82:97], v[190:193], v[106:109], v[82:97]
	v_mfma_f32_32x32x16_bf16 v[66:81], v[194:197], v[106:109], v[66:81]
	v_mfma_f32_32x32x16_bf16 v[50:65], v[198:201], v[106:109], v[50:65]
	v_mfma_f32_32x32x16_bf16 v[34:49], v[202:205], v[106:109], v[34:49]
	ds_read_b128 v[190:193], v180 offset:128
	ds_read_b128 v[194:197], v180 offset:6784
	ds_read_b128 v[198:201], v180 offset:13440
	ds_read_b128 v[202:205], v180 offset:20096
	v_mfma_f32_32x32x16_bf16 v[82:97], v[146:149], v[110:113], v[82:97]
	v_mfma_f32_32x32x16_bf16 v[66:81], v[150:153], v[110:113], v[66:81]
	v_mfma_f32_32x32x16_bf16 v[50:65], v[182:185], v[110:113], v[50:65]
	v_mfma_f32_32x32x16_bf16 v[34:49], v[186:189], v[110:113], v[34:49]
	ds_read_b128 v[146:149], v180 offset:160
	ds_read_b128 v[150:153], v180 offset:6816
	ds_read_b128 v[182:185], v180 offset:13472
	ds_read_b128 v[186:189], v180 offset:20128
	s_waitcnt lgkmcnt(0)
	v_mfma_f32_32x32x16_bf16 v[82:97], v[190:193], v[114:117], v[82:97]
	v_mfma_f32_32x32x16_bf16 v[66:81], v[194:197], v[114:117], v[66:81]
	v_mfma_f32_32x32x16_bf16 v[50:65], v[198:201], v[114:117], v[50:65]
	v_mfma_f32_32x32x16_bf16 v[34:49], v[202:205], v[114:117], v[34:49]
	v_mfma_f32_32x32x16_bf16 v[82:97], v[146:149], v[118:121], v[82:97]
	v_mfma_f32_32x32x16_bf16 v[66:81], v[150:153], v[118:121], v[66:81]
	v_mfma_f32_32x32x16_bf16 v[50:65], v[182:185], v[118:121], v[50:65]
	v_mfma_f32_32x32x16_bf16 v[34:49], v[186:189], v[118:121], v[34:49]
	s_setprio 0
	s_nop 10
	v_max_f32_e32 v146, v34, v34
	v_max_f32_e32 v147, v50, v50
	v_max_f32_e32 v146, v147, v146
	v_max3_f32 v146, v82, v66, v146
	v_max3_f32 v146, v146, v83, v67
	v_max3_f32 v146, v146, v51, v35
	v_max3_f32 v146, v146, v84, v68
	v_max3_f32 v146, v146, v52, v36
	v_max3_f32 v146, v146, v85, v69
	v_max3_f32 v146, v146, v53, v37
	v_max3_f32 v146, v146, v86, v70
	v_max3_f32 v146, v146, v54, v38
	v_max3_f32 v146, v146, v87, v71
	v_max3_f32 v146, v146, v55, v39
	v_max3_f32 v146, v146, v88, v72
	v_max3_f32 v146, v146, v56, v40
	v_max3_f32 v146, v146, v89, v73
	v_max3_f32 v146, v146, v57, v41
	v_max3_f32 v146, v146, v90, v74
	v_max3_f32 v146, v146, v58, v42
	v_max3_f32 v146, v146, v91, v75
	v_max3_f32 v146, v146, v59, v43
	v_max3_f32 v146, v146, v92, v76
	v_max3_f32 v146, v146, v60, v44
	v_max3_f32 v146, v146, v93, v77
	v_max3_f32 v146, v146, v61, v45
	v_max3_f32 v146, v146, v94, v78
	v_max3_f32 v146, v146, v62, v46
	v_max3_f32 v146, v146, v95, v79
	v_max3_f32 v146, v146, v63, v47
	v_max3_f32 v146, v146, v96, v80
	v_max3_f32 v146, v146, v64, v48
	v_max3_f32 v146, v146, v97, v81
	v_max3_f32 v182, v146, v65, v49
	ds_bpermute_b32 v183, v174, v182
	v_add_u32_e32 v180, s51, v161
	ds_read_b64_tr_b16 v[150:151], v180 offset:53248
	ds_read_b64_tr_b16 v[152:153], v180 offset:53760
	ds_read_b64_tr_b16 v[146:147], v180 offset:57344
	ds_read_b64_tr_b16 v[148:149], v180 offset:57856
	s_waitcnt lgkmcnt(0)
	v_max_f32_e32 v183, v183, v183
	v_max_f32_e32 v182, v182, v183
	v_cmp_gt_f32_e32 vcc, v182, v222
	s_cbranch_vccz .LBB0_152
; __device__ __forceinline__ void attn_unit_mla(LAS unsigned char* lds, const AttnDesc& A, int tid_in, int wid, int lane_in) {
;     ...
;         if (__builtin_amdgcn_ballot_w64(mx > mrun + 8.0f) != 0ull) {
;             const float mnew = fmaxf(mrun, mx);
;             const float alpha = __builtin_amdgcn_exp2f(mrun - mnew);
;             mrun = mnew; lrun *= alpha;
; #pragma unroll
;             for (int r = 0; r < 16; ++r) { o0[r] *= alpha; o1[r] *= alpha; }
;         }
	v_sub_f32_e32 v182, v182, v206
	v_max_f32_e32 v182, v182, v182
	v_max_f32_e32 v183, v179, v179
	v_max_f32_e32 v183, v183, v182
	v_sub_f32_e32 v179, v179, v183
	v_exp_f32_e32 v182, v179
	v_mov_b32_e32 v179, v183
	v_add_f32_e32 v184, v183, v206
	v_cmp_lt_f32_e32 vcc, 0xefa18f08, v183
	v_mov_b32_e32 v186, 0x41000000
	v_pk_mul_f32 v[16:17], v[16:17], v[182:183] op_sel_hi:[1,0]
	v_pk_mul_f32 v[14:15], v[14:15], v[182:183] op_sel_hi:[1,0]
	v_pk_mul_f32 v[12:13], v[12:13], v[182:183] op_sel_hi:[1,0]
	v_pk_mul_f32 v[10:11], v[10:11], v[182:183] op_sel_hi:[1,0]
	v_pk_mul_f32 v[8:9], v[8:9], v[182:183] op_sel_hi:[1,0]
	v_pk_mul_f32 v[6:7], v[6:7], v[182:183] op_sel_hi:[1,0]
	v_pk_mul_f32 v[4:5], v[4:5], v[182:183] op_sel_hi:[1,0]
	v_pk_mul_f32 v[2:3], v[2:3], v[182:183] op_sel_hi:[1,0]
	v_pk_mul_f32 v[32:33], v[32:33], v[182:183] op_sel_hi:[1,0]
	v_pk_mul_f32 v[30:31], v[30:31], v[182:183] op_sel_hi:[1,0]
	v_pk_mul_f32 v[28:29], v[28:29], v[182:183] op_sel_hi:[1,0]
	v_pk_mul_f32 v[26:27], v[26:27], v[182:183] op_sel_hi:[1,0]
	v_pk_mul_f32 v[24:25], v[24:25], v[182:183] op_sel_hi:[1,0]
	v_pk_mul_f32 v[22:23], v[22:23], v[182:183] op_sel_hi:[1,0]
	v_pk_mul_f32 v[20:21], v[20:21], v[182:183] op_sel_hi:[1,0]
	v_pk_mul_f32 v[18:19], v[18:19], v[182:183] op_sel_hi:[1,0]
	v_mul_f32_e32 v178, v178, v182
	v_cndmask_b32_e32 v185, 0, v183, vcc
	v_cndmask_b32_e32 v222, v241, v186, vcc
	v_sub_f32_e32 v34, v34, v184
	v_sub_f32_e32 v35, v35, v184
	v_sub_f32_e32 v36, v36, v184
	v_sub_f32_e32 v37, v37, v184
	v_sub_f32_e32 v38, v38, v184
	v_sub_f32_e32 v39, v39, v184
	v_sub_f32_e32 v40, v40, v184
	v_sub_f32_e32 v41, v41, v184
	v_sub_f32_e32 v42, v42, v184
	v_sub_f32_e32 v43, v43, v184
	v_sub_f32_e32 v44, v44, v184
	v_sub_f32_e32 v45, v45, v184
	v_sub_f32_e32 v46, v46, v184
	v_sub_f32_e32 v47, v47, v184
	v_sub_f32_e32 v48, v48, v184
	v_sub_f32_e32 v49, v49, v184
	v_sub_f32_e32 v50, v50, v184
	v_sub_f32_e32 v51, v51, v184
	v_sub_f32_e32 v52, v52, v184
	v_sub_f32_e32 v53, v53, v184
	v_sub_f32_e32 v54, v54, v184
	v_sub_f32_e32 v55, v55, v184
	v_sub_f32_e32 v56, v56, v184
	v_sub_f32_e32 v57, v57, v184
	v_sub_f32_e32 v58, v58, v184
	v_sub_f32_e32 v59, v59, v184
	v_sub_f32_e32 v60, v60, v184
	v_sub_f32_e32 v61, v61, v184
	v_sub_f32_e32 v62, v62, v184
	v_sub_f32_e32 v63, v63, v184
	v_sub_f32_e32 v64, v64, v184
	v_sub_f32_e32 v65, v65, v184
	v_sub_f32_e32 v66, v66, v184
	v_sub_f32_e32 v67, v67, v184
	v_sub_f32_e32 v68, v68, v184
	v_sub_f32_e32 v69, v69, v184
	v_sub_f32_e32 v70, v70, v184
	v_sub_f32_e32 v71, v71, v184
	v_sub_f32_e32 v72, v72, v184
	v_sub_f32_e32 v73, v73, v184
	v_sub_f32_e32 v74, v74, v184
	v_sub_f32_e32 v75, v75, v184
	v_sub_f32_e32 v76, v76, v184
	v_sub_f32_e32 v77, v77, v184
	v_sub_f32_e32 v78, v78, v184
	v_sub_f32_e32 v79, v79, v184
	v_sub_f32_e32 v80, v80, v184
	v_sub_f32_e32 v81, v81, v184
	v_sub_f32_e32 v82, v82, v184
	v_sub_f32_e32 v83, v83, v184
	v_sub_f32_e32 v84, v84, v184
	v_sub_f32_e32 v85, v85, v184
	v_sub_f32_e32 v86, v86, v184
	v_sub_f32_e32 v87, v87, v184
	v_sub_f32_e32 v88, v88, v184
	v_sub_f32_e32 v89, v89, v184
	v_sub_f32_e32 v90, v90, v184
	v_sub_f32_e32 v91, v91, v184
	v_sub_f32_e32 v92, v92, v184
	v_sub_f32_e32 v93, v93, v184
	v_sub_f32_e32 v94, v94, v184
	v_sub_f32_e32 v95, v95, v184
	v_sub_f32_e32 v96, v96, v184
	v_sub_f32_e32 v97, v97, v184
	v_sub_f32_e32 v206, 0, v185
	v_sub_f32_e32 v207, 0, v185
	v_sub_f32_e32 v208, 0, v185
	v_sub_f32_e32 v209, 0, v185
	v_sub_f32_e32 v210, 0, v185
	v_sub_f32_e32 v211, 0, v185
	v_sub_f32_e32 v212, 0, v185
	v_sub_f32_e32 v213, 0, v185
	v_sub_f32_e32 v214, 0, v185
	v_sub_f32_e32 v215, 0, v185
	v_sub_f32_e32 v216, 0, v185
	v_sub_f32_e32 v217, 0, v185
	v_sub_f32_e32 v218, 0, v185
	v_sub_f32_e32 v219, 0, v185
	v_sub_f32_e32 v220, 0, v185
	v_sub_f32_e32 v221, 0, v185
	s_branch .LBB0_152
